# v28 + warm-up loads ahead of the serialized 16-wide causal-pool window chain (pass 1)
# speedup vs baseline: 1.0135x; 1.0135x over previous
; #define LAS __attribute__((address_space(3)))
; __device__ __forceinline__ float bflo(unsigned w) { return __uint_as_float(w << 16); }
; __device__ __forceinline__ float bfhi(unsigned w) { return __uint_as_float(w & 0xffff0000u); }
; __device__ __forceinline__ u32x4 pack8(const f32x4 a, const f32x4 b) { u32x4 w; w.x = cvt_pk_bf16(a[0], a[1]); w.y = cvt_pk_bf16(a[2], a[3]); w.z = cvt_pk_bf16(b[0], b[1]); w.w = cvt_pk_bf16(b[2], b[3]); return w; }
; template <int WIN> __device__ __forceinline__ void pool_subtile(LAS unsigned char* vw, const bf16_t* up  , int s0, int lane) {
;     const int cg = lane & 15, tq = lane >> 4, sf = s0 + 4 * tq;
;     u32x4 rw[WIN + 3];
; #pragma unroll
;     for (int r = 0; r < WIN + 3; ++r) { const int sp = sf - (WIN - 1) + r; rw[r] = *(const u32x4*)(up + (size_t)max(sp, 0) * P1W); if (sp < 0) rw[r] = (u32x4){0u, 0u, 0u, 0u}; }
;     f32x4 s0v = (f32x4){0.f, 0.f, 0.f, 0.f}, s1v = s0v;
; #pragma unroll
;     for (int r = 0; r < WIN - 1; ++r) { s0v += (f32x4){bflo(rw[r].x), bfhi(rw[r].x), bflo(rw[r].y), bfhi(rw[r].y)}; s1v += (f32x4){bflo(rw[r].z), bfhi(rw[r].z), bflo(rw[r].w), bfhi(rw[r].w)}; }
; #pragma unroll
;     for (int jj = 0; jj < 4; ++jj) {
;         const u32x4 e = rw[jj + WIN - 1]; const f32x4 e0 = (f32x4){bflo(e.x), bfhi(e.x), bflo(e.y), bfhi(e.y)}, e1 = (f32x4){bflo(e.z), bfhi(e.z), bflo(e.w), bfhi(e.w)};
;         s0v += e0; s1v += e1;
;         const float inv = 1.0f / (float)min(sf + jj + 1, WIN);
;         *(LAS u32x4*)(vw + (4 * tq + jj) * WROW + cg * 16) = pack8(s0v * inv - e0, s1v * inv - e1);
;         const u32x4 o = rw[jj]; s0v -= (f32x4){bflo(o.x), bfhi(o.x), bflo(o.y), bfhi(o.y)}; s1v -= (f32x4){bflo(o.z), bfhi(o.z), bflo(o.w), bfhi(o.w)};
;     }
; }
; __device__ __forceinline__ void pool_items(LAS unsigned char* lds, LAS unsigned char* vw, int g, int wi, int nw, const MixP& p, int lane) {
;     ...
;             if (g == 0) pool_subtile<2>(vw, up, s0, lane); else if (g == 1) pool_subtile<4>(vw, up, s0, lane); else if (g == 2) pool_subtile<8>(vw, up, s0, lane); else pool_subtile<16>(vw, up, s0, lane);
.LBB0_677:
	s_xor_b64 s[58:59], s[8:9], -1
	s_or_b32 s55, s10, s29
	v_or_b32_e32 v78, s55, v238
	s_cmp_lt_i32 s89, 2
	s_mov_b64 s[8:9], -1
	s_cbranch_scc1 .LBB0_683
	v_sub_u32_e64 v10, v78, 7 clamp
	v_sub_u32_e64 v11, v78, 6 clamp
	v_sub_u32_e64 v12, v78, 5 clamp
	v_sub_u32_e64 v13, v78, 4 clamp
	s_mov_b64 s[12:13], -1
	s_cmp_gt_i32 s89, 2
	v_cmp_lt_u32_e64 s[10:11], 6, v78
	v_cmp_lt_u32_e64 s[8:9], 5, v78
	v_cmp_lt_u32_e32 vcc, 4, v78
	v_or_b32_e32 v79, 3, v78
	v_mul_u32_u24_e32 v36, 0xe00, v10
	v_mul_u32_u24_e32 v34, 0xe00, v11
	v_mul_u32_u24_e32 v32, 0xe00, v12
	v_mul_u32_u24_e32 v28, 0xe00, v13
	v_mad_u32_u24 v26, v78, s82, v219
	s_cbranch_scc0 .LBB0_680
	s_movk_i32 s100, 0xe00
	v_sub_u32_e64 v210, v78, 14 clamp
	v_mad_u64_u32 v[206:207], s[98:99], v210, s100, v[30:31]
	global_load_dword v211, v[206:207], off
	v_sub_u32_e64 v210, v78, 13 clamp
	v_mad_u64_u32 v[206:207], s[98:99], v210, s100, v[30:31]
	global_load_dword v211, v[206:207], off
	v_sub_u32_e64 v210, v78, 12 clamp
	v_mad_u64_u32 v[206:207], s[98:99], v210, s100, v[30:31]
	global_load_dword v211, v[206:207], off
	v_sub_u32_e64 v210, v78, 11 clamp
	v_mad_u64_u32 v[206:207], s[98:99], v210, s100, v[30:31]
	global_load_dword v211, v[206:207], off
	v_sub_u32_e64 v210, v78, 10 clamp
	v_mad_u64_u32 v[206:207], s[98:99], v210, s100, v[30:31]
	global_load_dword v211, v[206:207], off
	v_sub_u32_e64 v210, v78, 9 clamp
	v_mad_u64_u32 v[206:207], s[98:99], v210, s100, v[30:31]
	global_load_dword v211, v[206:207], off
	v_sub_u32_e64 v210, v78, 8 clamp
	v_mad_u64_u32 v[206:207], s[98:99], v210, s100, v[30:31]
	global_load_dword v211, v[206:207], off
	v_sub_u32_e64 v210, v78, 7 clamp
	v_mad_u64_u32 v[206:207], s[98:99], v210, s100, v[30:31]
	global_load_dword v211, v[206:207], off
	v_sub_u32_e64 v210, v78, 6 clamp
	v_mad_u64_u32 v[206:207], s[98:99], v210, s100, v[30:31]
	global_load_dword v211, v[206:207], off
	v_sub_u32_e64 v210, v78, 5 clamp
	v_mad_u64_u32 v[206:207], s[98:99], v210, s100, v[30:31]
	global_load_dword v211, v[206:207], off
	v_sub_u32_e64 v210, v78, 4 clamp
	v_mad_u64_u32 v[206:207], s[98:99], v210, s100, v[30:31]
	global_load_dword v211, v[206:207], off
	v_sub_u32_e64 v210, v78, 3 clamp
	v_mad_u64_u32 v[206:207], s[98:99], v210, s100, v[30:31]
	global_load_dword v211, v[206:207], off
	v_sub_u32_e64 v210, v78, 2 clamp
	v_mad_u64_u32 v[206:207], s[98:99], v210, s100, v[30:31]
	global_load_dword v211, v[206:207], off
	v_sub_u32_e64 v210, v78, 1 clamp
	v_mad_u64_u32 v[206:207], s[98:99], v210, s100, v[30:31]
	global_load_dword v211, v[206:207], off
	v_sub_u32_e64 v210, v78, 0 clamp
	v_mad_u64_u32 v[206:207], s[98:99], v210, s100, v[30:31]
	global_load_dword v211, v[206:207], off
	v_sub_u32_e64 v10, v78, 15 clamp
	v_mul_u32_u24_e32 v10, 0xe00, v10
	v_mov_b32_e32 v11, v1
	v_lshl_add_u64 v[10:11], v[30:31], 0, v[10:11]
	global_load_dwordx4 v[10:13], v[10:11], off
	v_cmp_lt_u32_e64 s[12:13], 14, v78
	v_mov_b32_e32 v37, v1
	v_mov_b32_e32 v35, v1
	v_mov_b32_e32 v33, v1
	v_mov_b32_e32 v29, v1
	v_mov_b32_e32 v27, v1
	v_or_b32_e32 v151, 1, v78
	v_or_b32_e32 v127, 2, v78
	s_waitcnt vmcnt(0)
	v_cndmask_b32_e64 v43, 0, v10, s[12:13]
	v_sub_u32_e64 v10, v78, 14 clamp
	v_cndmask_b32_e64 v41, 0, v11, s[12:13]
	v_mul_u32_u24_e32 v10, 0xe00, v10
	v_mov_b32_e32 v11, v1
	v_lshl_add_u64 v[10:11], v[30:31], 0, v[10:11]
	v_cndmask_b32_e64 v38, 0, v13, s[12:13]
	v_cndmask_b32_e64 v39, 0, v12, s[12:13]
	global_load_dwordx4 v[10:13], v[10:11], off
	v_cmp_lt_u32_e64 s[12:13], 13, v78
	v_lshlrev_b32_e32 v54, 16, v43
	v_and_b32_e32 v55, 0xffff0000, v43
	v_lshlrev_b32_e32 v56, 16, v41
	v_and_b32_e32 v57, 0xffff0000, v41
	v_pk_add_f32 v[50:51], v[56:57], 0 op_sel_hi:[1,0]
	v_pk_add_f32 v[52:53], v[54:55], 0 op_sel_hi:[1,0]
	v_lshlrev_b32_e32 v58, 16, v39
	v_and_b32_e32 v59, 0xffff0000, v39
	v_lshlrev_b32_e32 v60, 16, v38
	v_and_b32_e32 v61, 0xffff0000, v38
	v_pk_add_f32 v[38:39], v[60:61], 0 op_sel_hi:[1,0]
	v_pk_add_f32 v[128:129], v[58:59], 0 op_sel_hi:[1,0]
	s_waitcnt vmcnt(0)
	v_cndmask_b32_e64 v47, 0, v10, s[12:13]
	v_sub_u32_e64 v10, v78, 13 clamp
	v_cndmask_b32_e64 v44, 0, v11, s[12:13]
	v_mul_u32_u24_e32 v10, 0xe00, v10
	v_mov_b32_e32 v11, v1
	v_lshl_add_u64 v[10:11], v[30:31], 0, v[10:11]
	v_cndmask_b32_e64 v40, 0, v13, s[12:13]
	v_cndmask_b32_e64 v42, 0, v12, s[12:13]
	global_load_dwordx4 v[10:13], v[10:11], off
	v_cmp_lt_u32_e64 s[12:13], 12, v78
	v_lshlrev_b32_e32 v46, 16, v47
	v_and_b32_e32 v47, 0xffff0000, v47
	v_lshlrev_b32_e32 v48, 16, v44
	v_and_b32_e32 v49, 0xffff0000, v44
	v_pk_add_f32 v[138:139], v[52:53], v[46:47]
	v_pk_add_f32 v[140:141], v[50:51], v[48:49]
	v_lshlrev_b32_e32 v50, 16, v42
	v_and_b32_e32 v51, 0xffff0000, v42
	v_lshlrev_b32_e32 v52, 16, v40
	v_and_b32_e32 v53, 0xffff0000, v40
	v_pk_add_f32 v[128:129], v[128:129], v[50:51]
	v_pk_add_f32 v[152:153], v[38:39], v[52:53]
	s_waitcnt vmcnt(0)
	v_cndmask_b32_e64 v84, 0, v10, s[12:13]
	v_sub_u32_e64 v10, v78, 12 clamp
	v_cndmask_b32_e64 v82, 0, v11, s[12:13]
	v_mul_u32_u24_e32 v10, 0xe00, v10
	v_mov_b32_e32 v11, v1
	v_lshl_add_u64 v[10:11], v[30:31], 0, v[10:11]
	v_cndmask_b32_e64 v45, 0, v13, s[12:13]
	v_cndmask_b32_e64 v80, 0, v12, s[12:13]
	global_load_dwordx4 v[10:13], v[10:11], off
	v_cmp_lt_u32_e64 s[12:13], 11, v78
	v_lshlrev_b32_e32 v40, 16, v82
	v_and_b32_e32 v41, 0xffff0000, v82
	v_lshlrev_b32_e32 v42, 16, v80
	v_and_b32_e32 v43, 0xffff0000, v80
	v_lshlrev_b32_e32 v44, 16, v45
	v_and_b32_e32 v45, 0xffff0000, v45
	v_pk_add_f32 v[140:141], v[140:141], v[40:41]
	v_pk_add_f32 v[152:153], v[152:153], v[44:45]
	v_pk_add_f32 v[128:129], v[128:129], v[42:43]
	v_lshlrev_b32_e32 v38, 16, v84
	v_and_b32_e32 v39, 0xffff0000, v84
	v_pk_add_f32 v[138:139], v[138:139], v[38:39]
	s_waitcnt vmcnt(0)
; __device__ __forceinline__ float bflo(unsigned w) { return __uint_as_float(w << 16); }
; __device__ __forceinline__ float bfhi(unsigned w) { return __uint_as_float(w & 0xffff0000u); }
; template <int WIN> __device__ __forceinline__ void pool_subtile(LAS unsigned char* vw, const bf16_t* up  , int s0, int lane) {
;     ...
;     for (int r = 0; r < WIN + 3; ++r) { const int sp = sf - (WIN - 1) + r; rw[r] = *(const u32x4*)(up + (size_t)max(sp, 0) * P1W); if (sp < 0) rw[r] = (u32x4){0u, 0u, 0u, 0u}; }
;     f32x4 s0v = (f32x4){0.f, 0.f, 0.f, 0.f}, s1v = s0v;
; #pragma unroll
;     for (int r = 0; r < WIN - 1; ++r) { s0v += (f32x4){bflo(rw[r].x), bfhi(rw[r].x), bflo(rw[r].y), bfhi(rw[r].y)}; s1v += (f32x4){bflo(rw[r].z), bfhi(rw[r].z), bflo(rw[r].w), bfhi(rw[r].w)}; }
	v_cndmask_b32_e64 v88, 0, v10, s[12:13]
	v_sub_u32_e64 v10, v78, 11 clamp
	v_cndmask_b32_e64 v86, 0, v11, s[12:13]
	v_mul_u32_u24_e32 v10, 0xe00, v10
	v_mov_b32_e32 v11, v1
	v_lshl_add_u64 v[10:11], v[30:31], 0, v[10:11]
	v_cndmask_b32_e64 v81, 0, v13, s[12:13]
	v_cndmask_b32_e64 v83, 0, v12, s[12:13]
	global_load_dwordx4 v[10:13], v[10:11], off
	v_cmp_lt_u32_e64 s[12:13], 10, v78
	v_lshlrev_b32_e32 v156, 16, v86
	v_and_b32_e32 v157, 0xffff0000, v86
	v_lshlrev_b32_e32 v82, 16, v83
	v_and_b32_e32 v83, 0xffff0000, v83
	v_lshlrev_b32_e32 v80, 16, v81
	v_and_b32_e32 v81, 0xffff0000, v81
	v_pk_add_f32 v[140:141], v[140:141], v[156:157]
	v_pk_add_f32 v[82:83], v[128:129], v[82:83]
	v_pk_add_f32 v[80:81], v[152:153], v[80:81]
	v_lshlrev_b32_e32 v154, 16, v88
	v_and_b32_e32 v155, 0xffff0000, v88
	v_pk_add_f32 v[138:139], v[138:139], v[154:155]
	s_waitcnt vmcnt(0)
	v_cndmask_b32_e64 v92, 0, v10, s[12:13]
	v_sub_u32_e64 v10, v78, 10 clamp
	v_cndmask_b32_e64 v90, 0, v11, s[12:13]
	v_mul_u32_u24_e32 v10, 0xe00, v10
	v_mov_b32_e32 v11, v1
	v_lshl_add_u64 v[10:11], v[30:31], 0, v[10:11]
	v_cndmask_b32_e64 v85, 0, v13, s[12:13]
	v_cndmask_b32_e64 v87, 0, v12, s[12:13]
	global_load_dwordx4 v[10:13], v[10:11], off
	v_cmp_lt_u32_e64 s[12:13], 9, v78
	v_lshlrev_b32_e32 v152, 16, v90
	v_and_b32_e32 v153, 0xffff0000, v90
	v_lshlrev_b32_e32 v86, 16, v87
	v_and_b32_e32 v87, 0xffff0000, v87
	v_pk_add_f32 v[140:141], v[140:141], v[152:153]
	v_lshlrev_b32_e32 v84, 16, v85
	v_and_b32_e32 v85, 0xffff0000, v85
	v_pk_add_f32 v[82:83], v[82:83], v[86:87]
	v_pk_add_f32 v[80:81], v[80:81], v[84:85]
	v_lshlrev_b32_e32 v128, 16, v92
	v_and_b32_e32 v129, 0xffff0000, v92
	v_pk_add_f32 v[128:129], v[138:139], v[128:129]
	s_waitcnt vmcnt(0)
	v_cndmask_b32_e64 v96, 0, v10, s[12:13]
	v_sub_u32_e64 v10, v78, 9 clamp
	v_cndmask_b32_e64 v94, 0, v11, s[12:13]
	v_mul_u32_u24_e32 v10, 0xe00, v10
	v_mov_b32_e32 v11, v1
	v_lshl_add_u64 v[10:11], v[30:31], 0, v[10:11]
	v_cndmask_b32_e64 v89, 0, v13, s[12:13]
	v_cndmask_b32_e64 v91, 0, v12, s[12:13]
	global_load_dwordx4 v[10:13], v[10:11], off
	v_cmp_lt_u32_e64 s[12:13], 8, v78
	v_lshlrev_b32_e32 v86, 16, v94
	v_and_b32_e32 v87, 0xffff0000, v94
	v_lshlrev_b32_e32 v90, 16, v91
	v_and_b32_e32 v91, 0xffff0000, v91
	v_pk_add_f32 v[86:87], v[140:141], v[86:87]
	v_lshlrev_b32_e32 v88, 16, v89
	v_and_b32_e32 v89, 0xffff0000, v89
	v_pk_add_f32 v[82:83], v[82:83], v[90:91]
	v_pk_add_f32 v[80:81], v[80:81], v[88:89]
	v_lshlrev_b32_e32 v84, 16, v96
	v_and_b32_e32 v85, 0xffff0000, v96
	v_pk_add_f32 v[84:85], v[128:129], v[84:85]
	s_waitcnt vmcnt(0)
	v_cndmask_b32_e64 v100, 0, v10, s[12:13]
	v_sub_u32_e64 v10, v78, 8 clamp
	v_cndmask_b32_e64 v98, 0, v11, s[12:13]
	v_mul_u32_u24_e32 v10, 0xe00, v10
	v_mov_b32_e32 v11, v1
	v_lshl_add_u64 v[10:11], v[30:31], 0, v[10:11]
	v_cndmask_b32_e64 v93, 0, v13, s[12:13]
	v_cndmask_b32_e64 v95, 0, v12, s[12:13]
	global_load_dwordx4 v[10:13], v[10:11], off
	v_cmp_lt_u32_e64 s[12:13], 7, v78
	v_lshlrev_b32_e32 v90, 16, v98
	v_and_b32_e32 v91, 0xffff0000, v98
	v_pk_add_f32 v[86:87], v[86:87], v[90:91]
	v_lshlrev_b32_e32 v90, 16, v93
	v_and_b32_e32 v91, 0xffff0000, v93
	v_pk_add_f32 v[80:81], v[80:81], v[90:91]
	v_lshlrev_b32_e32 v88, 16, v100
	v_and_b32_e32 v89, 0xffff0000, v100
	v_pk_add_f32 v[84:85], v[84:85], v[88:89]
	v_lshlrev_b32_e32 v88, 16, v95
	v_and_b32_e32 v89, 0xffff0000, v95
	v_pk_add_f32 v[82:83], v[82:83], v[88:89]
	s_waitcnt vmcnt(0)
	v_cndmask_b32_e64 v102, 0, v11, s[12:13]
	v_cndmask_b32_e64 v103, 0, v10, s[12:13]
	v_lshl_add_u64 v[10:11], v[30:31], 0, v[36:37]
	v_cndmask_b32_e64 v97, 0, v13, s[12:13]
	v_cndmask_b32_e64 v99, 0, v12, s[12:13]
	global_load_dwordx4 v[10:13], v[10:11], off
	v_lshlrev_b32_e32 v90, 16, v102
	v_and_b32_e32 v91, 0xffff0000, v102
	v_pk_add_f32 v[86:87], v[86:87], v[90:91]
	v_lshlrev_b32_e32 v90, 16, v97
	v_and_b32_e32 v91, 0xffff0000, v97
	v_pk_add_f32 v[80:81], v[80:81], v[90:91]
	v_lshlrev_b32_e32 v88, 16, v103
	v_and_b32_e32 v89, 0xffff0000, v103
	v_pk_add_f32 v[84:85], v[84:85], v[88:89]
	v_lshlrev_b32_e32 v88, 16, v99
	v_and_b32_e32 v89, 0xffff0000, v99
	v_pk_add_f32 v[82:83], v[82:83], v[88:89]
	s_mov_b64 s[12:13], 0
	s_waitcnt vmcnt(0)
	v_cndmask_b32_e64 v106, 0, v11, s[10:11]
	v_cndmask_b32_e64 v107, 0, v10, s[10:11]
	v_lshl_add_u64 v[10:11], v[30:31], 0, v[34:35]
	v_cndmask_b32_e64 v37, 0, v13, s[10:11]
	v_cndmask_b32_e64 v101, 0, v12, s[10:11]
	global_load_dwordx4 v[10:13], v[10:11], off
	v_lshlrev_b32_e32 v90, 16, v106
	v_and_b32_e32 v91, 0xffff0000, v106
	v_pk_add_f32 v[86:87], v[86:87], v[90:91]
	v_lshlrev_b32_e32 v90, 16, v37
	v_and_b32_e32 v91, 0xffff0000, v37
	v_pk_add_f32 v[80:81], v[80:81], v[90:91]
	v_lshlrev_b32_e32 v88, 16, v107
	v_and_b32_e32 v89, 0xffff0000, v107
	v_pk_add_f32 v[84:85], v[84:85], v[88:89]
	v_lshlrev_b32_e32 v88, 16, v101
	v_and_b32_e32 v89, 0xffff0000, v101
	v_pk_add_f32 v[82:83], v[82:83], v[88:89]
	s_waitcnt vmcnt(0)
	v_cndmask_b32_e64 v108, 0, v11, s[8:9]
	v_cndmask_b32_e64 v110, 0, v10, s[8:9]
	v_lshl_add_u64 v[10:11], v[30:31], 0, v[32:33]
	v_cndmask_b32_e64 v35, 0, v13, s[8:9]
	v_cndmask_b32_e64 v104, 0, v12, s[8:9]
	global_load_dwordx4 v[10:13], v[10:11], off
	v_lshlrev_b32_e32 v90, 16, v108
	v_and_b32_e32 v91, 0xffff0000, v108
	v_pk_add_f32 v[86:87], v[86:87], v[90:91]
	v_lshlrev_b32_e32 v90, 16, v35
	v_and_b32_e32 v91, 0xffff0000, v35
	v_pk_add_f32 v[80:81], v[80:81], v[90:91]
	v_lshlrev_b32_e32 v88, 16, v110
	v_and_b32_e32 v89, 0xffff0000, v110
	v_pk_add_f32 v[84:85], v[84:85], v[88:89]
	v_lshlrev_b32_e32 v88, 16, v104
	v_and_b32_e32 v89, 0xffff0000, v104
	v_pk_add_f32 v[82:83], v[82:83], v[88:89]
	s_waitcnt vmcnt(0)
; __device__ __forceinline__ float bflo(unsigned w) { return __uint_as_float(w << 16); }
; __device__ __forceinline__ float bfhi(unsigned w) { return __uint_as_float(w & 0xffff0000u); }
; template <int WIN> __device__ __forceinline__ void pool_subtile(LAS unsigned char* vw, const bf16_t* up  , int s0, int lane) {
;     ...
;     for (int r = 0; r < WIN + 3; ++r) { const int sp = sf - (WIN - 1) + r; rw[r] = *(const u32x4*)(up + (size_t)max(sp, 0) * P1W); if (sp < 0) rw[r] = (u32x4){0u, 0u, 0u, 0u}; }
;     f32x4 s0v = (f32x4){0.f, 0.f, 0.f, 0.f}, s1v = s0v;
; #pragma unroll
;     for (int r = 0; r < WIN - 1; ++r) { s0v += (f32x4){bflo(rw[r].x), bfhi(rw[r].x), bflo(rw[r].y), bfhi(rw[r].y)}; s1v += (f32x4){bflo(rw[r].z), bfhi(rw[r].z), bflo(rw[r].w), bfhi(rw[r].w)}; }
; #pragma unroll
;     for (int jj = 0; jj < 4; ++jj) {
;         const u32x4 e = rw[jj + WIN - 1]; const f32x4 e0 = (f32x4){bflo(e.x), bfhi(e.x), bflo(e.y), bfhi(e.y)}, e1 = (f32x4){bflo(e.z), bfhi(e.z), bflo(e.w), bfhi(e.w)};
;         s0v += e0; s1v += e1;
;         const float inv = 1.0f / (float)min(sf + jj + 1, WIN);
	v_cndmask_b32_e32 v111, 0, v11, vcc
	v_cndmask_b32_e32 v112, 0, v10, vcc
	v_lshl_add_u64 v[10:11], v[30:31], 0, v[28:29]
	v_cndmask_b32_e32 v33, 0, v13, vcc
	v_cndmask_b32_e32 v105, 0, v12, vcc
	global_load_dwordx4 v[10:13], v[10:11], off
	v_cmp_eq_u32_e32 vcc, 0, v78
	v_lshlrev_b32_e32 v90, 16, v111
	v_and_b32_e32 v91, 0xffff0000, v111
	v_pk_add_f32 v[86:87], v[86:87], v[90:91]
	v_lshlrev_b32_e32 v90, 16, v33
	v_and_b32_e32 v91, 0xffff0000, v33
	v_pk_add_f32 v[80:81], v[80:81], v[90:91]
	v_lshlrev_b32_e32 v88, 16, v112
	v_and_b32_e32 v89, 0xffff0000, v112
	v_pk_add_f32 v[84:85], v[84:85], v[88:89]
	v_lshlrev_b32_e32 v88, 16, v105
	v_and_b32_e32 v89, 0xffff0000, v105
	v_pk_add_f32 v[82:83], v[82:83], v[88:89]
	s_waitcnt vmcnt(0)
	v_cndmask_b32_e64 v114, v10, 0, vcc
	v_sub_u32_e64 v10, v78, 3 clamp
	v_cndmask_b32_e64 v113, v11, 0, vcc
	v_mul_u32_u24_e32 v10, 0xe00, v10
	v_mov_b32_e32 v11, v1
	v_lshl_add_u64 v[10:11], v[30:31], 0, v[10:11]
	v_cndmask_b32_e64 v29, v13, 0, vcc
	v_cndmask_b32_e64 v109, v12, 0, vcc
	global_load_dwordx4 v[10:13], v[10:11], off
	v_lshlrev_b32_e32 v90, 16, v113
	v_and_b32_e32 v91, 0xffff0000, v113
	v_pk_add_f32 v[86:87], v[86:87], v[90:91]
	v_lshlrev_b32_e32 v90, 16, v29
	v_and_b32_e32 v91, 0xffff0000, v29
	v_lshlrev_b32_e32 v88, 16, v114
	v_and_b32_e32 v89, 0xffff0000, v114
	v_pk_add_f32 v[84:85], v[84:85], v[88:89]
	v_lshlrev_b32_e32 v88, 16, v109
	v_and_b32_e32 v89, 0xffff0000, v109
	v_pk_add_f32 v[82:83], v[82:83], v[88:89]
	v_pk_add_f32 v[80:81], v[80:81], v[90:91]
	s_waitcnt vmcnt(0)
	v_cndmask_b32_e64 v118, v10, 0, vcc
	v_sub_u32_e64 v10, v78, 2 clamp
	v_cndmask_b32_e64 v117, v11, 0, vcc
	v_mul_u32_u24_e32 v10, 0xe00, v10
	v_mov_b32_e32 v11, v1
	v_lshl_add_u64 v[10:11], v[30:31], 0, v[10:11]
	v_cndmask_b32_e64 v115, v13, 0, vcc
	v_cndmask_b32_e64 v116, v12, 0, vcc
	global_load_dwordx4 v[10:13], v[10:11], off
	v_lshlrev_b32_e32 v88, 16, v118
	v_and_b32_e32 v89, 0xffff0000, v118
	v_lshlrev_b32_e32 v90, 16, v117
	v_and_b32_e32 v91, 0xffff0000, v117
	v_pk_add_f32 v[86:87], v[86:87], v[90:91]
	v_pk_add_f32 v[84:85], v[84:85], v[88:89]
	v_lshlrev_b32_e32 v88, 16, v116
	v_and_b32_e32 v89, 0xffff0000, v116
	v_lshlrev_b32_e32 v90, 16, v115
	v_and_b32_e32 v91, 0xffff0000, v115
	v_pk_add_f32 v[80:81], v[80:81], v[90:91]
	v_pk_add_f32 v[82:83], v[82:83], v[88:89]
	s_waitcnt vmcnt(0)
	v_cndmask_b32_e64 v123, v10, 0, vcc
	v_sub_u32_e64 v10, v78, 1 clamp
	v_cndmask_b32_e64 v121, v11, 0, vcc
	v_mul_u32_u24_e32 v10, 0xe00, v10
	v_mov_b32_e32 v11, v1
	v_lshl_add_u64 v[10:11], v[30:31], 0, v[10:11]
	v_cndmask_b32_e64 v119, v13, 0, vcc
	v_cndmask_b32_e64 v120, v12, 0, vcc
	global_load_dwordx4 v[10:13], v[10:11], off
	v_lshlrev_b32_e32 v88, 16, v123
	v_and_b32_e32 v89, 0xffff0000, v123
	v_lshlrev_b32_e32 v90, 16, v121
	v_and_b32_e32 v91, 0xffff0000, v121
	v_pk_add_f32 v[84:85], v[84:85], v[88:89]
	v_pk_add_f32 v[86:87], v[86:87], v[90:91]
	v_lshlrev_b32_e32 v88, 16, v120
	v_and_b32_e32 v89, 0xffff0000, v120
	v_lshlrev_b32_e32 v90, 16, v119
	v_and_b32_e32 v91, 0xffff0000, v119
	v_pk_add_f32 v[82:83], v[82:83], v[88:89]
	v_pk_add_f32 v[80:81], v[80:81], v[90:91]
	s_waitcnt vmcnt(0)
	v_cndmask_b32_e64 v125, v11, 0, vcc
	v_cndmask_b32_e64 v126, v10, 0, vcc
	v_mul_u32_u24_e32 v10, 0xe00, v78
	v_mov_b32_e32 v11, v1
	v_lshl_add_u64 v[10:11], v[30:31], 0, v[10:11]
	global_load_dwordx4 v[22:25], v[10:11], off
	global_load_dwordx4 v[18:21], v[10:11], off offset:3584
	v_mad_u32_u24 v10, v78, s82, v218
	v_mov_b32_e32 v11, v1
	v_lshl_add_u64 v[10:11], v[30:31], 0, v[10:11]
	global_load_dwordx4 v[14:17], v[10:11], off
	v_lshl_add_u64 v[10:11], v[30:31], 0, v[26:27]
	v_cndmask_b32_e64 v122, v13, 0, vcc
	v_cndmask_b32_e64 v124, v12, 0, vcc
	global_load_dwordx4 v[10:13], v[10:11], off
	v_min_u32_e32 v27, 15, v78
	v_add_u32_e32 v27, 1, v27
	v_cvt_f32_ubyte0_e32 v27, v27
	v_div_scale_f32 v29, s[8:9], v27, v27, 1.0
	v_rcp_f32_e32 v33, v29
	v_lshlrev_b32_e32 v88, 16, v126
	v_and_b32_e32 v89, 0xffff0000, v126
	v_lshlrev_b32_e32 v90, 16, v125
	v_fma_f32 v35, -v29, v33, 1.0
	v_fmac_f32_e32 v33, v35, v33
	v_div_scale_f32 v35, vcc, 1.0, v27, 1.0
	v_mul_f32_e32 v37, v35, v33
	v_fma_f32 v92, -v29, v37, v35
	v_fmac_f32_e32 v37, v92, v33
	v_fma_f32 v29, -v29, v37, v35
	v_div_fmas_f32 v29, v29, v33, v37
	v_div_fixup_f32 v92, v29, v27, 1.0
	v_min_u32_e32 v29, 15, v151
	v_add_u32_e32 v29, 1, v29
	v_cvt_f32_ubyte0_e32 v29, v29
	v_and_b32_e32 v91, 0xffff0000, v125
	v_div_scale_f32 v33, s[8:9], v29, v29, 1.0
	v_pk_add_f32 v[86:87], v[86:87], v[90:91]
	v_pk_add_f32 v[84:85], v[84:85], v[88:89]
	v_lshlrev_b32_e32 v88, 16, v124
	v_and_b32_e32 v89, 0xffff0000, v124
	v_lshlrev_b32_e32 v90, 16, v122
	v_and_b32_e32 v91, 0xffff0000, v122
	v_rcp_f32_e32 v35, v33
	v_pk_add_f32 v[80:81], v[80:81], v[90:91]
	v_pk_add_f32 v[82:83], v[82:83], v[88:89]
	v_add_u32_e32 v27, v225, v239
	v_fma_f32 v37, -v33, v35, 1.0
	v_fmac_f32_e32 v35, v37, v35
	v_div_scale_f32 v37, vcc, 1.0, v29, 1.0
	s_waitcnt vmcnt(3)
; #define LAS __attribute__((address_space(3)))
; __device__ __forceinline__ float bflo(unsigned w) { return __uint_as_float(w << 16); }
; __device__ __forceinline__ float bfhi(unsigned w) { return __uint_as_float(w & 0xffff0000u); }
; __device__ __forceinline__ u32x4 pack8(const f32x4 a, const f32x4 b) { u32x4 w; w.x = cvt_pk_bf16(a[0], a[1]); w.y = cvt_pk_bf16(a[2], a[3]); w.z = cvt_pk_bf16(b[0], b[1]); w.w = cvt_pk_bf16(b[2], b[3]); return w; }
; template <int WIN> __device__ __forceinline__ void pool_subtile(LAS unsigned char* vw, const bf16_t* up  , int s0, int lane) {
;     ...
;     for (int jj = 0; jj < 4; ++jj) {
;         const u32x4 e = rw[jj + WIN - 1]; const f32x4 e0 = (f32x4){bflo(e.x), bfhi(e.x), bflo(e.y), bfhi(e.y)}, e1 = (f32x4){bflo(e.z), bfhi(e.z), bflo(e.w), bfhi(e.w)};
;         s0v += e0; s1v += e1;
;         const float inv = 1.0f / (float)min(sf + jj + 1, WIN);
;         *(LAS u32x4*)(vw + (4 * tq + jj) * WROW + cg * 16) = pack8(s0v * inv - e0, s1v * inv - e1);
;         const u32x4 o = rw[jj]; s0v -= (f32x4){bflo(o.x), bfhi(o.x), bflo(o.y), bfhi(o.y)}; s1v -= (f32x4){bflo(o.z), bfhi(o.z), bflo(o.w), bfhi(o.w)};
;     }
	v_lshlrev_b32_e32 v88, 16, v22
	v_and_b32_e32 v89, 0xffff0000, v22
	v_lshlrev_b32_e32 v22, 16, v23
	v_and_b32_e32 v23, 0xffff0000, v23
	v_lshlrev_b32_e32 v90, 16, v24
	v_and_b32_e32 v91, 0xffff0000, v24
	v_lshlrev_b32_e32 v24, 16, v25
	v_and_b32_e32 v25, 0xffff0000, v25
	v_pk_add_f32 v[86:87], v[86:87], v[22:23]
	v_pk_add_f32 v[80:81], v[80:81], v[24:25]
	v_xor_b32_e32 v23, 0x80000000, v23
	v_xor_b32_e32 v22, 0x80000000, v22
	v_xor_b32_e32 v25, 0x80000000, v25
	v_xor_b32_e32 v24, 0x80000000, v24
	v_pk_add_f32 v[84:85], v[84:85], v[88:89]
	v_pk_add_f32 v[82:83], v[82:83], v[90:91]
	v_pk_fma_f32 v[94:95], v[92:93], v[86:87], v[22:23] op_sel_hi:[0,1,1]
	v_xor_b32_e32 v23, 0x80000000, v89
	v_xor_b32_e32 v22, 0x80000000, v88
	v_pk_fma_f32 v[88:89], v[92:93], v[80:81], v[24:25] op_sel_hi:[0,1,1]
	v_xor_b32_e32 v25, 0x80000000, v91
	v_xor_b32_e32 v24, 0x80000000, v90
	v_pk_fma_f32 v[22:23], v[92:93], v[84:85], v[22:23] op_sel_hi:[0,1,1]
	v_pk_fma_f32 v[24:25], v[92:93], v[82:83], v[24:25] op_sel_hi:[0,1,1]
	v_cvt_pk_bf16_f32 v22, v22, v23
	v_cvt_pk_bf16_f32 v23, v94, v95
	v_cvt_pk_bf16_f32 v24, v24, v25
	v_cvt_pk_bf16_f32 v25, v88, v89
	ds_write_b128 v27, v[22:25]
	v_sub_f32_e32 v24, v84, v54
	v_sub_f32_e32 v54, v80, v60
	v_mul_f32_e32 v80, v37, v35
	v_sub_f32_e32 v25, v85, v55
	v_sub_f32_e32 v55, v81, v61
	v_fma_f32 v81, -v33, v80, v37
	v_fmac_f32_e32 v80, v81, v35
	v_fma_f32 v33, -v33, v80, v37
	v_div_fmas_f32 v33, v33, v35, v80
	v_div_fixup_f32 v80, v33, v29, 1.0
	v_min_u32_e32 v29, 15, v127
	v_add_u32_e32 v29, 1, v29
	v_cvt_f32_ubyte0_e32 v29, v29
	v_div_scale_f32 v33, s[8:9], v29, v29, 1.0
	v_rcp_f32_e32 v35, v33
	v_sub_f32_e32 v23, v87, v57
	v_sub_f32_e32 v22, v86, v56
	v_sub_f32_e32 v57, v83, v59
	v_sub_f32_e32 v56, v82, v58
	s_waitcnt vmcnt(2)
	v_lshlrev_b32_e32 v58, 16, v18
	v_and_b32_e32 v59, 0xffff0000, v18
	v_lshlrev_b32_e32 v18, 16, v19
	v_and_b32_e32 v19, 0xffff0000, v19
	v_lshlrev_b32_e32 v60, 16, v20
	v_and_b32_e32 v61, 0xffff0000, v20
	v_lshlrev_b32_e32 v20, 16, v21
	v_and_b32_e32 v21, 0xffff0000, v21
	v_pk_add_f32 v[22:23], v[22:23], v[18:19]
	v_pk_add_f32 v[54:55], v[54:55], v[20:21]
	v_xor_b32_e32 v19, 0x80000000, v19
	v_xor_b32_e32 v18, 0x80000000, v18
	v_xor_b32_e32 v21, 0x80000000, v21
	v_xor_b32_e32 v20, 0x80000000, v20
	v_pk_add_f32 v[24:25], v[24:25], v[58:59]
	v_pk_add_f32 v[56:57], v[56:57], v[60:61]
	v_pk_fma_f32 v[82:83], v[80:81], v[22:23], v[18:19] op_sel_hi:[0,1,1]
	v_xor_b32_e32 v19, 0x80000000, v59
	v_xor_b32_e32 v18, 0x80000000, v58
	v_pk_fma_f32 v[58:59], v[80:81], v[54:55], v[20:21] op_sel_hi:[0,1,1]
	v_xor_b32_e32 v21, 0x80000000, v61
	v_xor_b32_e32 v20, 0x80000000, v60
	v_pk_fma_f32 v[18:19], v[80:81], v[24:25], v[18:19] op_sel_hi:[0,1,1]
	v_pk_fma_f32 v[20:21], v[80:81], v[56:57], v[20:21] op_sel_hi:[0,1,1]
	v_fma_f32 v37, -v33, v35, 1.0
	v_cvt_pk_bf16_f32 v18, v18, v19
	v_cvt_pk_bf16_f32 v19, v82, v83
	v_cvt_pk_bf16_f32 v20, v20, v21
	v_fmac_f32_e32 v35, v37, v35
	v_div_scale_f32 v37, vcc, 1.0, v29, 1.0
	v_cvt_pk_bf16_f32 v21, v58, v59
	ds_write_b128 v27, v[18:21] offset:272
	v_sub_f32_e32 v20, v24, v46
	v_sub_f32_e32 v24, v56, v50
	v_mul_f32_e32 v50, v37, v35
	v_sub_f32_e32 v21, v25, v47
	v_sub_f32_e32 v25, v57, v51
	v_fma_f32 v51, -v33, v50, v37
	v_fmac_f32_e32 v50, v51, v35
	v_fma_f32 v33, -v33, v50, v37
	v_sub_f32_e32 v19, v23, v49
	v_sub_f32_e32 v18, v22, v48
	v_sub_f32_e32 v23, v55, v53
	v_sub_f32_e32 v22, v54, v52
	s_waitcnt vmcnt(1)
	v_lshlrev_b32_e32 v46, 16, v14
	v_and_b32_e32 v47, 0xffff0000, v14
	v_lshlrev_b32_e32 v14, 16, v15
	v_and_b32_e32 v15, 0xffff0000, v15
	v_lshlrev_b32_e32 v48, 16, v16
	v_and_b32_e32 v49, 0xffff0000, v16
	v_lshlrev_b32_e32 v16, 16, v17
	v_and_b32_e32 v17, 0xffff0000, v17
	v_div_fmas_f32 v33, v33, v35, v50
	v_pk_add_f32 v[18:19], v[18:19], v[14:15]
	v_pk_add_f32 v[22:23], v[22:23], v[16:17]
	v_div_fixup_f32 v50, v33, v29, 1.0
	v_xor_b32_e32 v15, 0x80000000, v15
	v_xor_b32_e32 v14, 0x80000000, v14
	v_xor_b32_e32 v17, 0x80000000, v17
	v_xor_b32_e32 v16, 0x80000000, v16
	v_pk_add_f32 v[20:21], v[20:21], v[46:47]
	v_pk_add_f32 v[24:25], v[24:25], v[48:49]
	v_pk_fma_f32 v[52:53], v[50:51], v[18:19], v[14:15] op_sel_hi:[0,1,1]
	v_xor_b32_e32 v15, 0x80000000, v47
	v_xor_b32_e32 v14, 0x80000000, v46
	v_pk_fma_f32 v[46:47], v[50:51], v[22:23], v[16:17] op_sel_hi:[0,1,1]
	v_xor_b32_e32 v17, 0x80000000, v49
	v_xor_b32_e32 v16, 0x80000000, v48
	v_pk_fma_f32 v[14:15], v[50:51], v[20:21], v[14:15] op_sel_hi:[0,1,1]
	v_pk_fma_f32 v[16:17], v[50:51], v[24:25], v[16:17] op_sel_hi:[0,1,1]
	v_cvt_pk_bf16_f32 v14, v14, v15
	v_cvt_pk_bf16_f32 v15, v52, v53
	v_cvt_pk_bf16_f32 v16, v16, v17
	v_cvt_pk_bf16_f32 v17, v46, v47
	ds_write_b128 v27, v[14:17] offset:544
	v_min_u32_e32 v27, 15, v79
	v_add_u32_e32 v27, 1, v27
	v_cvt_f32_ubyte0_e32 v27, v27
	v_div_scale_f32 v29, s[8:9], v27, v27, 1.0
	v_rcp_f32_e32 v33, v29
	v_sub_f32_e32 v16, v20, v38
	v_sub_f32_e32 v15, v19, v41
	v_sub_f32_e32 v14, v18, v40
	v_fma_f32 v35, -v29, v33, 1.0
	v_fmac_f32_e32 v33, v35, v33
	v_div_scale_f32 v35, vcc, 1.0, v27, 1.0
	v_mul_f32_e32 v37, v35, v33
	v_fma_f32 v38, -v29, v37, v35
	v_fmac_f32_e32 v37, v38, v33
	v_fma_f32 v29, -v29, v37, v35
	v_sub_f32_e32 v19, v23, v45
	v_sub_f32_e32 v18, v22, v44
	s_waitcnt vmcnt(0)
	v_lshlrev_b32_e32 v22, 16, v10
	v_and_b32_e32 v23, 0xffff0000, v10
	v_lshlrev_b32_e32 v10, 16, v11
	v_and_b32_e32 v11, 0xffff0000, v11
	v_div_fmas_f32 v29, v29, v33, v37
	v_sub_f32_e32 v17, v21, v39
	v_sub_f32_e32 v21, v25, v43
	v_sub_f32_e32 v20, v24, v42
	v_lshlrev_b32_e32 v24, 16, v12
	v_and_b32_e32 v25, 0xffff0000, v12
	v_lshlrev_b32_e32 v12, 16, v13
	v_and_b32_e32 v13, 0xffff0000, v13
	v_pk_add_f32 v[14:15], v[14:15], v[10:11]
	v_div_fixup_f32 v38, v29, v27, 1.0
	v_xor_b32_e32 v11, 0x80000000, v11
	v_xor_b32_e32 v10, 0x80000000, v10
	v_pk_add_f32 v[16:17], v[16:17], v[22:23]
	v_pk_add_f32 v[18:19], v[18:19], v[12:13]
	v_pk_fma_f32 v[14:15], v[38:39], v[14:15], v[10:11] op_sel_hi:[0,1,1]
	v_xor_b32_e32 v11, 0x80000000, v23
	v_xor_b32_e32 v10, 0x80000000, v22
	v_xor_b32_e32 v13, 0x80000000, v13
	v_xor_b32_e32 v12, 0x80000000, v12
	v_pk_add_f32 v[20:21], v[20:21], v[24:25]
	v_pk_fma_f32 v[10:11], v[38:39], v[16:17], v[10:11] op_sel_hi:[0,1,1]
	v_pk_fma_f32 v[16:17], v[38:39], v[18:19], v[12:13] op_sel_hi:[0,1,1]
	v_xor_b32_e32 v13, 0x80000000, v25
	v_xor_b32_e32 v12, 0x80000000, v24
	v_pk_fma_f32 v[12:13], v[38:39], v[20:21], v[12:13] op_sel_hi:[0,1,1]
	v_cvt_pk_bf16_f32 v10, v10, v11
	v_cvt_pk_bf16_f32 v11, v14, v15
	v_cvt_pk_bf16_f32 v12, v12, v13
	v_cvt_pk_bf16_f32 v13, v16, v17
